# as the combined version but waves 4-7 run the next item's TW/AD tiles before their products and waves 0-3 after
# baseline (speedup 1.0000x reference)
.LBB0_294:
	v_mov_b32_e32 v137, v29
	s_nop 5
	v_cvt_pk_bf16_f32 v48, v78, v79
	v_cvt_pk_bf16_f32 v49, v80, v81
	v_lshl_add_u64 v[26:27], v[26:27], 0, v[136:137]
	global_store_dwordx2 v[26:27], v[48:49], off nt
	v_add_u32_e32 v26, v194, v200
	ds_read_b128 v[78:81], v26
	s_cmp_lg_u32 s51, s72
	s_waitcnt lgkmcnt(0)
	v_mfma_f32_16x16x32_bf16 v[74:77], v[74:77], v[78:81], 0
	ds_read_b128 v[78:81], v26 offset:64
	ds_read_b32 v26, v201
	s_waitcnt lgkmcnt(1)
	v_mfma_f32_16x16x32_bf16 v[70:73], v[70:73], v[78:81], v[74:77]
	s_nop 7
	v_pk_add_f32 v[48:49], v[126:127], v[70:71]
	v_pk_add_f32 v[70:71], v[130:131], v[72:73]
	s_waitcnt lgkmcnt(0)
	v_pk_mul_f32 v[48:49], v[26:27], v[48:49] op_sel_hi:[0,1]
	v_pk_mul_f32 v[26:27], v[26:27], v[70:71] op_sel_hi:[0,1]
	v_cvt_pk_bf16_f32 v48, v48, v49
	v_cvt_pk_bf16_f32 v49, v26, v27
	v_lshl_add_u64 v[26:27], v[124:125], 1, s[26:27]
	global_store_dwordx2 v[26:27], v[48:49], off nt
	v_add_u32_e32 v26, v190, v200
	ds_read_b128 v[70:73], v26
	v_add_u32_e32 v27, v195, v199
	ds_read_b128 v[74:77], v27 offset:10240
	s_waitcnt lgkmcnt(1)
	v_mfma_f32_16x16x32_bf16 v[70:73], v[94:97], v[70:73], 0
	s_waitcnt lgkmcnt(0)
	v_mfma_f32_16x16x32_bf16 v[70:73], v[98:101], v[74:77], v[70:73]
	ds_read_b128 v[74:77], v26 offset:64
	s_waitcnt lgkmcnt(0)
	v_mfma_f32_16x16x32_bf16 v[70:73], v[90:93], v[74:77], v[70:73]
	ds_read_b128 v[74:77], v27 offset:10304
	s_waitcnt lgkmcnt(0)
	v_mfma_f32_16x16x32_bf16 v[70:73], v[86:89], v[74:77], v[70:73]
	s_nop 7
	v_pk_mul_f32 v[26:27], v[68:69], v[72:73]
	v_pk_mul_f32 v[48:49], v[66:67], v[70:71]
	s_nop 0
	v_cvt_pk_bf16_f32 v48, v48, v49
	v_cvt_pk_bf16_f32 v49, v26, v27
	v_lshl_add_u64 v[26:27], v[116:117], 1, s[24:25]
	global_store_dwordx2 v[26:27], v[48:49], off nt
	v_readfirstlane_b32 s36, v0
	s_cmp_lt_u32 s36, 0x100
	s_cbranch_scc0 .Ltw_end
	s_waitcnt vmcnt(8)

.Ltw_skip:
	v_readfirstlane_b32 s36, v0
	s_cmp_lt_u32 s36, 0x100
	s_cbranch_scc0 .Ltw_prod

.LBB0_395:
	ds_read_b128 v[94:97], v215 offset:10240
	ds_read_b128 v[98:101], v215 offset:11264
	ds_read_b128 v[102:105], v215 offset:12288
	ds_read_b128 v[106:109], v215 offset:13312
	s_waitcnt lgkmcnt(11)
	v_cvt_pk_bf16_f32 v48, v48, v49
	s_waitcnt lgkmcnt(3)
	v_cvt_pk_bf16_f32 v94, v94, v95
	v_cvt_pk_bf16_f32 v95, v96, v97
	v_cvt_pk_bf16_f32 v49, v68, v69
	v_mov_b32_e32 v26, v78
	v_mov_b32_e32 v27, v79
	v_mov_b32_e32 v74, v80
	v_mov_b32_e32 v75, v81
	v_mfma_f32_16x16x16_bf16 v[78:81], v[94:95], v[48:49], 0
	v_mov_b32_e32 v28, v29
	s_waitcnt lgkmcnt(2)
	v_cvt_pk_bf16_f32 v96, v98, v99
	v_cvt_pk_bf16_f32 v97, v100, v101
	s_waitcnt lgkmcnt(1)
	v_cvt_pk_bf16_f32 v98, v102, v103
	s_nop 1
	v_xor_b32_e32 v47, 0x80000000, v79
	v_xor_b32_e32 v48, 0x80000000, v78
	v_cvt_pk_bf16_f32 v78, v48, v47
	v_xor_b32_e32 v47, 0x80000000, v80
	v_xor_b32_e32 v48, 0x80000000, v81
	v_cvt_pk_bf16_f32 v79, v47, v48
	v_mov_b32_e32 v80, v29
	v_mov_b32_e32 v81, v29
	v_cvt_pk_bf16_f32 v99, v104, v105
	v_mov_b32_e32 v68, v29
	v_mfma_f32_16x16x32_bf16 v[90:93], v[26:29], v[78:81], v[90:93]
	v_mov_b32_e32 v69, v29
	s_waitcnt lgkmcnt(0)
	v_cvt_pk_bf16_f32 v100, v106, v107
	v_cvt_pk_bf16_f32 v101, v108, v109
	s_nop 3
	v_cvt_pk_bf16_f32 v26, v90, v91
	v_cvt_pk_bf16_f32 v27, v92, v93
	s_andn2_b64 vcc, exec, s[62:63]
	s_nop 0
	v_mfma_f32_16x16x16_bf16 v[90:93], v[96:97], v[26:27], 0
	s_nop 7
	v_xor_b32_e32 v26, 0x80000000, v91
	v_xor_b32_e32 v27, 0x80000000, v90
	v_cvt_pk_bf16_f32 v80, v27, v26
	v_xor_b32_e32 v26, 0x80000000, v92
	v_xor_b32_e32 v27, 0x80000000, v93
	v_cvt_pk_bf16_f32 v81, v26, v27
	ds_write2_b64 v216, v[78:79], v[80:81] offset1:4
	s_nop 0
	v_mfma_f32_16x16x32_bf16 v[74:77], v[74:77], v[78:81], v[86:89]
	v_mfma_f32_16x16x32_bf16 v[70:73], v[70:73], v[78:81], v[82:85]
	s_nop 6
	v_cvt_pk_bf16_f32 v26, v74, v75
	v_cvt_pk_bf16_f32 v27, v76, v77
	s_nop 1
	v_mfma_f32_16x16x16_bf16 v[74:77], v[98:99], v[26:27], 0
	s_nop 7
	v_xor_b32_e32 v26, 0x80000000, v75
	v_xor_b32_e32 v27, 0x80000000, v74
	v_cvt_pk_bf16_f32 v26, v27, v26
	v_xor_b32_e32 v27, 0x80000000, v76
	v_xor_b32_e32 v28, 0x80000000, v77
	v_cvt_pk_bf16_f32 v27, v27, v28
	v_mov_b32_e32 v28, v29
	s_nop 1
	v_mfma_f32_16x16x32_bf16 v[66:69], v[66:69], v[26:29], v[70:73]
	s_nop 7
	v_cvt_pk_bf16_f32 v48, v66, v67
	v_cvt_pk_bf16_f32 v49, v68, v69
	s_nop 1
	v_mfma_f32_16x16x16_bf16 v[66:69], v[100:101], v[48:49], 0
	s_nop 7
	v_xor_b32_e32 v28, 0x80000000, v67
	v_xor_b32_e32 v47, 0x80000000, v66
	v_cvt_pk_bf16_f32 v48, v47, v28
	v_xor_b32_e32 v28, 0x80000000, v68
	v_xor_b32_e32 v47, 0x80000000, v69
	v_cvt_pk_bf16_f32 v49, v28, v47
	ds_write2_b64 v216, v[26:27], v[48:49] offset0:8 offset1:12
	s_waitcnt lgkmcnt(0)
	s_barrier
	v_readfirstlane_b32 s36, v0
	s_cmp_lt_u32 s36, 0x100
	s_cbranch_scc1 .Ltw_prod
	s_waitcnt vmcnt(0)
	s_branch .Ltw_do
